# P1: static s_setprio 1 for waves 4-7 in GEMM phases, per-segment flips removed (on C12)
# baseline (speedup 1.0000x reference)
.LBB0_277:
	s_and_b64 s[40:41], s[2:3], exec
	s_movk_i32 s21, 0x1400
	s_cselect_b32 s47, 0x800, s21
	v_readlane_b32 s21, v254, 54
	s_cmp_eq_u32 s21, 1
	s_cselect_b64 s[40:41], -1, 0
	s_cmp_eq_u32 s43, 8
	s_cselect_b32 s21, s73, s71
	v_writelane_b32 v255, s21, 30
	s_cselect_b32 s21, s72, s70
	s_cselect_b32 s46, s54, 0x400
	v_writelane_b32 v255, s21, 32
	s_and_b64 s[42:43], s[22:23], exec
	s_mov_b32 s21, 0x680000
	s_cselect_b32 s21, s21, 0x1180000
	s_and_b64 s[2:3], s[2:3], exec
	s_cselect_b32 s21, 0x480000, s21
	s_and_b64 s[2:3], s[26:27], exec
	s_cselect_b32 s2, 0, s21
	v_readlane_b32 s42, v255, 16
	v_readlane_b32 s43, v255, 17
	s_add_u32 s2, s42, s2
	v_writelane_b32 v255, s2, 34
	s_addc_u32 s2, s43, 0
	v_writelane_b32 v255, s2, 36
	s_andn2_b64 vcc, exec, s[10:11]
	v_cndmask_b32_e64 v142, 1.0, -1.0, s[40:41]
	s_cbranch_vccnz .LBB0_710
	s_waitcnt vmcnt(0)
	v_bfe_i32 v4, v0, 27, 1
	v_lshlrev_b32_e32 v2, 4, v0
	v_lshrrev_b32_e32 v4, 22, v4
	v_add_u32_e32 v4, v2, v4
	v_and_b32_e32 v4, 0xfffffc00, v4
	v_sub_u32_e32 v4, v2, v4
	v_ashrrev_i32_e32 v3, 31, v0
	v_lshrrev_b32_e32 v5, 4, v4
	v_lshrrev_b32_e32 v3, 26, v3
	v_bitop3_b32 v4, v5, v4, 32 bitop3:0x6c
	v_add_u32_e32 v3, v0, v3
	s_waitcnt vmcnt(2)
	v_ashrrev_i32_e32 v6, 31, v4
	v_ashrrev_i32_e32 v3, 6, v3
	v_lshrrev_b32_e32 v6, 26, v6
	v_lshlrev_b32_e32 v5, 3, v3
	v_add_u32_e32 v6, v4, v6
	v_and_b32_e32 v5, -16, v5
	v_ashrrev_i32_e32 v7, 6, v6
	v_lshlrev_b32_e32 v3, 5, v3
	v_add_u32_e32 v5, v7, v5
	s_waitcnt vmcnt(0)
	v_and_b32_e32 v14, 32, v3
	v_and_b32_e32 v3, 0xc0, v6
	v_sub_u32_e32 v3, v4, v3
	v_lshlrev_b32_e32 v4, 1, v5
	v_lshrrev_b32_e32 v6, 2, v5
	v_and_b32_e32 v7, 3, v7
	v_ashrrev_i16_sdwa v3, v178, sext(v3) dst_sel:DWORD dst_unused:UNUSED_PAD src0_sel:DWORD src1_sel:BYTE_0
	v_and_b32_e32 v4, 24, v4
	v_and_b32_e32 v6, 4, v6
	v_and_or_b32 v7, v5, s84, v7
	v_bfe_i32 v15, v3, 0, 16
	v_or3_b32 v4, v7, v6, v4
	v_add_u32_e32 v3, v14, v15
	v_mul_lo_u32 v16, v5, s46
	v_mul_lo_u32 v4, v4, s46
	v_add_u32_e32 v2, 0x2000, v2
	v_add_lshl_u32 v144, v3, v16, 1
	v_add_lshl_u32 v146, v4, v3, 1
	v_ashrrev_i32_e32 v3, 31, v2
	v_lshrrev_b32_e32 v3, 22, v3
	v_add_u32_e32 v3, v2, v3
	v_ashrrev_i32_e32 v3, 10, v3
	v_mul_i32_i24_e32 v4, 0x400, v3
	v_sub_u32_e32 v2, v2, v4
	v_lshrrev_b32_e32 v4, 4, v2
	v_bitop3_b32 v2, v4, v2, 32 bitop3:0x6c
	v_ashrrev_i32_e32 v5, 31, v2
	v_lshrrev_b32_e32 v5, 26, v5
	v_writelane_b32 v255, s44, 38
	v_lshlrev_b32_e32 v4, 3, v3
	v_add_u32_e32 v5, v2, v5
	v_writelane_b32 v255, s45, 39
	s_ashr_i32 s21, s20, 6
	v_and_b32_e32 v4, -16, v4
	v_ashrrev_i32_e32 v6, 6, v5
	v_lshlrev_b32_e32 v3, 5, v3
	s_lshl_b32 s78, s46, 9
	v_add_u32_e32 v4, v6, v4
	v_and_b32_e32 v17, 32, v3
	v_and_b32_e32 v3, 0xc0, v5
	s_ashr_i32 s40, s20, 8
	s_lshl_b32 s76, s46, 8
	s_lshl_b32 s79, s21, 10
	s_mul_i32 s10, s78, s28
	v_readlane_b32 s29, v255, 34
	v_sub_u32_e32 v2, v2, v3
	v_lshlrev_b32_e32 v3, 1, v4
	v_lshrrev_b32_e32 v5, 2, v4
	v_and_b32_e32 v6, 3, v6
	s_mul_hi_i32 s11, s78, s28
	s_add_u32 s10, s29, s10
	v_readlane_b32 s29, v255, 36
	v_ashrrev_i16_sdwa v2, v178, sext(v2) dst_sel:DWORD dst_unused:UNUSED_PAD src0_sel:DWORD src1_sel:BYTE_0
	v_and_b32_e32 v3, 24, v3
	v_and_b32_e32 v5, 4, v5
	v_and_or_b32 v6, v4, s84, v6
	s_addc_u32 s11, s29, s11
	s_add_i32 s29, s79, 0
	v_bfe_i32 v18, v2, 0, 16
	v_or3_b32 v3, v6, v5, v3
	s_add_i32 m0, s29, 0x10000
	v_add_u32_e32 v2, v17, v18
	v_mul_lo_u32 v3, v3, s46
	global_load_lds_dwordx4 v146, s[10:11]
	s_add_i32 m0, s29, 0x12000
	v_add_lshl_u32 v150, v3, v2, 1
	s_add_u32 s42, s10, s76
	global_load_lds_dwordx4 v150, s[10:11]
	s_addc_u32 s43, s11, 0
	s_add_i32 m0, s29, 0x14000
	s_mul_i32 s2, s78, s16
	global_load_lds_dwordx4 v146, s[42:43]
	s_add_i32 m0, s29, 0x16000
	v_readlane_b32 s41, v255, 32
	s_mul_hi_i32 s3, s78, s16
	s_add_u32 s2, s41, s2
	v_readlane_b32 s41, v255, 30
	s_addc_u32 s3, s41, s3
	s_add_i32 s93, s29, 0x2000
	v_mul_lo_u32 v19, v4, s46
	global_load_lds_dwordx4 v150, s[42:43]
	s_mov_b32 m0, s29
	s_add_u32 s44, s2, s76
	v_add_lshl_u32 v148, v2, v19, 1
	global_load_lds_dwordx4 v144, s[2:3]
	s_mov_b32 m0, s93
	s_addc_u32 s45, s3, 0
	s_add_i32 s52, s29, 0x4000
	global_load_lds_dwordx4 v148, s[2:3]
	s_mov_b32 m0, s52
	s_add_i32 s53, s29, 0x6000
	global_load_lds_dwordx4 v144, s[44:45]
	s_mov_b32 m0, s53
	v_mov_b32_e32 v147, v1
	global_load_lds_dwordx4 v148, s[44:45]
	v_mov_b32_e32 v151, v1
	s_cmp_eq_u32 s40, 1
	v_lshl_add_u64 v[4:5], s[42:43], 0, v[146:147]
	v_lshl_add_u64 v[2:3], s[42:43], 0, v[150:151]
	s_cselect_b64 s[42:43], -1, 0
	v_mov_b32_e32 v145, v1
	v_mov_b32_e32 v149, v1
	v_writelane_b32 v255, s42, 40
	s_mov_b32 s77, s17
	v_lshl_add_u64 v[10:11], s[10:11], 0, v[146:147]
	v_lshl_add_u64 v[6:7], s[10:11], 0, v[150:151]
	v_lshl_add_u64 v[8:9], s[2:3], 0, v[144:145]
	v_writelane_b32 v255, s43, 41
	s_cmp_lg_u32 s40, 1
	v_lshl_add_u64 v[12:13], s[2:3], 0, v[148:149]
	s_cbranch_scc1 .LBB0_280
	s_barrier
	s_setprio 1

.LBB0_294:
	s_add_i32 s22, s10, 2
	s_add_u32 s23, s2, 0x80
	s_addc_u32 s11, s3, 0
	s_add_i32 s41, 0, 0x10000
	s_cmp_eq_u32 s75, s10
	s_cselect_b32 s11, s83, s11
	s_cselect_b32 s10, s82, s23
	v_add_u32_e32 v0, s41, v153
	s_cselect_b32 s45, s95, s21
	s_cselect_b32 s44, s94, s20
	s_add_i32 s23, 0, 0x14000
	ds_read_b128 v[130:133], v0
	ds_read_b128 v[134:137], v0 offset:1024
	ds_read_b128 v[160:163], v0 offset:2048
	ds_read_b128 v[164:167], v0 offset:3072
	v_add_u32_e32 v0, s23, v153
	ds_read_b128 v[168:171], v0
	ds_read_b128 v[172:175], v0 offset:1024
	ds_read_b128 v[202:205], v0 offset:2048
	ds_read_b128 v[206:209], v0 offset:3072
	s_add_i32 m0, s29, 0xc000
	ds_read_b128 v[210:213], v201
	ds_read_b128 v[214:217], v201 offset:1024
	ds_read_b128 v[218:221], v201 offset:2048
	ds_read_b128 v[222:225], v201 offset:3072
	ds_read_b128 v[226:229], v201 offset:4096
	ds_read_b128 v[230:233], v201 offset:5120
	ds_read_b128 v[234:237], v201 offset:6144
	ds_read_b128 v[238:241], v201 offset:7168
	global_load_lds_dwordx4 v156, s[2:3]
	s_add_i32 m0, s29, 0xe000
	s_nop 0
	global_load_lds_dwordx4 v158, s[2:3]
	s_waitcnt vmcnt(8)
	s_waitcnt lgkmcnt(0)
	s_barrier
	s_waitcnt lgkmcnt(0)
	v_mfma_f32_16x16x32_bf16 v[126:129], v[130:133], v[210:213], v[126:129]
	v_mfma_f32_16x16x32_bf16 v[122:125], v[160:163], v[210:213], v[122:125]
	v_mfma_f32_16x16x32_bf16 v[110:113], v[130:133], v[218:221], v[110:113]
	v_mfma_f32_16x16x32_bf16 v[106:109], v[160:163], v[218:221], v[106:109]
	v_mfma_f32_16x16x32_bf16 v[94:97], v[130:133], v[226:229], v[94:97]
	v_mfma_f32_16x16x32_bf16 v[90:93], v[160:163], v[226:229], v[90:93]
	v_mfma_f32_16x16x32_bf16 v[78:81], v[130:133], v[234:237], v[78:81]
	v_mfma_f32_16x16x32_bf16 v[74:77], v[160:163], v[234:237], v[74:77]
	v_mfma_f32_16x16x32_bf16 v[126:129], v[134:137], v[214:217], v[126:129]
	v_mfma_f32_16x16x32_bf16 v[122:125], v[164:167], v[214:217], v[122:125]
	v_mfma_f32_16x16x32_bf16 v[110:113], v[134:137], v[222:225], v[110:113]
	v_mfma_f32_16x16x32_bf16 v[106:109], v[164:167], v[222:225], v[106:109]
	v_mfma_f32_16x16x32_bf16 v[94:97], v[134:137], v[230:233], v[94:97]
	v_mfma_f32_16x16x32_bf16 v[90:93], v[164:167], v[230:233], v[90:93]
	v_mfma_f32_16x16x32_bf16 v[78:81], v[134:137], v[238:241], v[78:81]
	v_mfma_f32_16x16x32_bf16 v[74:77], v[164:167], v[238:241], v[74:77]
	v_mfma_f32_16x16x32_bf16 v[118:121], v[168:171], v[210:213], v[118:121]
	v_mfma_f32_16x16x32_bf16 v[114:117], v[202:205], v[210:213], v[114:117]
	v_mfma_f32_16x16x32_bf16 v[102:105], v[168:171], v[218:221], v[102:105]
	v_mfma_f32_16x16x32_bf16 v[98:101], v[202:205], v[218:221], v[98:101]
	v_mfma_f32_16x16x32_bf16 v[86:89], v[168:171], v[226:229], v[86:89]
	v_mfma_f32_16x16x32_bf16 v[82:85], v[202:205], v[226:229], v[82:85]
	v_mfma_f32_16x16x32_bf16 v[70:73], v[168:171], v[234:237], v[70:73]
	v_mfma_f32_16x16x32_bf16 v[66:69], v[202:205], v[234:237], v[66:69]
	v_mfma_f32_16x16x32_bf16 v[118:121], v[172:175], v[214:217], v[118:121]
	v_mfma_f32_16x16x32_bf16 v[114:117], v[206:209], v[214:217], v[114:117]
	v_mfma_f32_16x16x32_bf16 v[102:105], v[172:175], v[222:225], v[102:105]
	v_mfma_f32_16x16x32_bf16 v[98:101], v[206:209], v[222:225], v[98:101]
	v_mfma_f32_16x16x32_bf16 v[86:89], v[172:175], v[230:233], v[86:89]
	v_mfma_f32_16x16x32_bf16 v[82:85], v[206:209], v[230:233], v[82:85]
	v_mfma_f32_16x16x32_bf16 v[70:73], v[172:175], v[238:241], v[70:73]
	v_mfma_f32_16x16x32_bf16 v[66:69], v[206:209], v[238:241], v[66:69]
	s_barrier
	s_add_i32 s41, s41, s79
	s_mov_b32 m0, s41
	ds_read_b128 v[210:213], v201 offset:16384
	ds_read_b128 v[214:217], v201 offset:17408
	ds_read_b128 v[218:221], v201 offset:18432
	ds_read_b128 v[222:225], v201 offset:19456
	ds_read_b128 v[226:229], v201 offset:20480
	ds_read_b128 v[230:233], v201 offset:21504
	ds_read_b128 v[234:237], v201 offset:22528
	ds_read_b128 v[238:241], v201 offset:23552
	global_load_lds_dwordx4 v146, s[44:45]
	s_add_i32 m0, s41, 0x2000
	s_add_u32 s98, s44, 0x80
	s_addc_u32 s99, s45, 0
	global_load_lds_dwordx4 v150, s[44:45]
	s_add_u32 s44, s44, s76
	s_addc_u32 s45, s45, 0
	s_add_i32 s23, s23, s79
	s_mov_b32 m0, s23
	s_add_u32 s100, s10, 0x80
	s_addc_u32 s101, s11, 0
	global_load_lds_dwordx4 v146, s[44:45]
	s_add_i32 m0, s23, 0x2000
	s_nop 0
	global_load_lds_dwordx4 v150, s[44:45]
	s_mov_b32 m0, s29
	s_nop 0
	global_load_lds_dwordx4 v144, s[10:11]
	s_mov_b32 m0, s93
	s_nop 0
	global_load_lds_dwordx4 v148, s[10:11]
	s_waitcnt vmcnt(8)
	s_waitcnt lgkmcnt(0)
	s_barrier
	s_waitcnt lgkmcnt(0)
	v_mfma_f32_16x16x32_bf16 v[62:65], v[130:133], v[210:213], v[62:65]
	v_mfma_f32_16x16x32_bf16 v[58:61], v[160:163], v[210:213], v[58:61]
	v_mfma_f32_16x16x32_bf16 v[46:49], v[130:133], v[218:221], v[46:49]
	v_mfma_f32_16x16x32_bf16 v[42:45], v[160:163], v[218:221], v[42:45]
	v_mfma_f32_16x16x32_bf16 v[30:33], v[130:133], v[226:229], v[30:33]
	v_mfma_f32_16x16x32_bf16 v[26:29], v[160:163], v[226:229], v[26:29]
	v_mfma_f32_16x16x32_bf16 v[14:17], v[130:133], v[234:237], v[14:17]
	v_mfma_f32_16x16x32_bf16 v[10:13], v[160:163], v[234:237], v[10:13]
	v_mfma_f32_16x16x32_bf16 v[62:65], v[134:137], v[214:217], v[62:65]
	v_mfma_f32_16x16x32_bf16 v[58:61], v[164:167], v[214:217], v[58:61]
	v_mfma_f32_16x16x32_bf16 v[46:49], v[134:137], v[222:225], v[46:49]
	v_mfma_f32_16x16x32_bf16 v[42:45], v[164:167], v[222:225], v[42:45]
	v_mfma_f32_16x16x32_bf16 v[30:33], v[134:137], v[230:233], v[30:33]
	v_mfma_f32_16x16x32_bf16 v[26:29], v[164:167], v[230:233], v[26:29]
	v_mfma_f32_16x16x32_bf16 v[14:17], v[134:137], v[238:241], v[14:17]
	v_mfma_f32_16x16x32_bf16 v[10:13], v[164:167], v[238:241], v[10:13]
	v_mfma_f32_16x16x32_bf16 v[54:57], v[168:171], v[210:213], v[54:57]
	v_mfma_f32_16x16x32_bf16 v[50:53], v[202:205], v[210:213], v[50:53]
	v_mfma_f32_16x16x32_bf16 v[38:41], v[168:171], v[218:221], v[38:41]
	v_mfma_f32_16x16x32_bf16 v[34:37], v[202:205], v[218:221], v[34:37]
	v_mfma_f32_16x16x32_bf16 v[22:25], v[168:171], v[226:229], v[22:25]
	v_mfma_f32_16x16x32_bf16 v[18:21], v[202:205], v[226:229], v[18:21]
	v_mfma_f32_16x16x32_bf16 v[6:9], v[168:171], v[234:237], v[6:9]
	v_mfma_f32_16x16x32_bf16 v[2:5], v[202:205], v[234:237], v[2:5]
	v_mfma_f32_16x16x32_bf16 v[54:57], v[172:175], v[214:217], v[54:57]
	v_mfma_f32_16x16x32_bf16 v[50:53], v[206:209], v[214:217], v[50:53]
	v_mfma_f32_16x16x32_bf16 v[38:41], v[172:175], v[222:225], v[38:41]
	v_mfma_f32_16x16x32_bf16 v[34:37], v[206:209], v[222:225], v[34:37]
	v_mfma_f32_16x16x32_bf16 v[22:25], v[172:175], v[230:233], v[22:25]
	v_mfma_f32_16x16x32_bf16 v[18:21], v[206:209], v[230:233], v[18:21]
	v_mfma_f32_16x16x32_bf16 v[6:9], v[172:175], v[238:241], v[6:9]
	v_mfma_f32_16x16x32_bf16 v[2:5], v[206:209], v[238:241], v[2:5]
	s_barrier
	s_add_i32 s23, 0, 0x18000
	v_add_u32_e32 v0, s23, v153
	s_add_i32 s41, 0, 0x1c000
	ds_read_b128 v[130:133], v0
	ds_read_b128 v[134:137], v0 offset:1024
	ds_read_b128 v[160:163], v0 offset:2048
	ds_read_b128 v[164:167], v0 offset:3072
	v_add_u32_e32 v0, s41, v153
	ds_read_b128 v[168:171], v0
	ds_read_b128 v[172:175], v0 offset:1024
	ds_read_b128 v[202:205], v0 offset:2048
	ds_read_b128 v[206:209], v0 offset:3072
	s_add_u32 s10, s10, s76
	s_addc_u32 s11, s11, 0
	s_mov_b32 m0, s52
	ds_read_b128 v[210:213], v201 offset:32768
	ds_read_b128 v[214:217], v201 offset:33792
	ds_read_b128 v[218:221], v201 offset:34816
	ds_read_b128 v[222:225], v201 offset:35840
	ds_read_b128 v[226:229], v201 offset:36864
	ds_read_b128 v[230:233], v201 offset:37888
	ds_read_b128 v[234:237], v201 offset:38912
	ds_read_b128 v[238:241], v201 offset:39936
	global_load_lds_dwordx4 v144, s[10:11]
	s_mov_b32 m0, s53
	s_nop 0
	global_load_lds_dwordx4 v148, s[10:11]
	s_waitcnt vmcnt(8)
	s_waitcnt lgkmcnt(0)
	s_barrier
	s_waitcnt lgkmcnt(0)
	v_mfma_f32_16x16x32_bf16 v[126:129], v[130:133], v[210:213], v[126:129]
	v_mfma_f32_16x16x32_bf16 v[122:125], v[160:163], v[210:213], v[122:125]
	v_mfma_f32_16x16x32_bf16 v[110:113], v[130:133], v[218:221], v[110:113]
	v_mfma_f32_16x16x32_bf16 v[106:109], v[160:163], v[218:221], v[106:109]
	v_mfma_f32_16x16x32_bf16 v[94:97], v[130:133], v[226:229], v[94:97]
	v_mfma_f32_16x16x32_bf16 v[90:93], v[160:163], v[226:229], v[90:93]
	v_mfma_f32_16x16x32_bf16 v[78:81], v[130:133], v[234:237], v[78:81]
	v_mfma_f32_16x16x32_bf16 v[74:77], v[160:163], v[234:237], v[74:77]
	v_mfma_f32_16x16x32_bf16 v[126:129], v[134:137], v[214:217], v[126:129]
	v_mfma_f32_16x16x32_bf16 v[122:125], v[164:167], v[214:217], v[122:125]
	v_mfma_f32_16x16x32_bf16 v[110:113], v[134:137], v[222:225], v[110:113]
	v_mfma_f32_16x16x32_bf16 v[106:109], v[164:167], v[222:225], v[106:109]
	v_mfma_f32_16x16x32_bf16 v[94:97], v[134:137], v[230:233], v[94:97]
	v_mfma_f32_16x16x32_bf16 v[90:93], v[164:167], v[230:233], v[90:93]
	v_mfma_f32_16x16x32_bf16 v[78:81], v[134:137], v[238:241], v[78:81]
	v_mfma_f32_16x16x32_bf16 v[74:77], v[164:167], v[238:241], v[74:77]
	v_mfma_f32_16x16x32_bf16 v[118:121], v[168:171], v[210:213], v[118:121]
	v_mfma_f32_16x16x32_bf16 v[114:117], v[202:205], v[210:213], v[114:117]
	v_mfma_f32_16x16x32_bf16 v[102:105], v[168:171], v[218:221], v[102:105]
	v_mfma_f32_16x16x32_bf16 v[98:101], v[202:205], v[218:221], v[98:101]
	v_mfma_f32_16x16x32_bf16 v[86:89], v[168:171], v[226:229], v[86:89]
	v_mfma_f32_16x16x32_bf16 v[82:85], v[202:205], v[226:229], v[82:85]
	v_mfma_f32_16x16x32_bf16 v[70:73], v[168:171], v[234:237], v[70:73]
	v_mfma_f32_16x16x32_bf16 v[66:69], v[202:205], v[234:237], v[66:69]
	v_mfma_f32_16x16x32_bf16 v[118:121], v[172:175], v[214:217], v[118:121]
	v_mfma_f32_16x16x32_bf16 v[114:117], v[206:209], v[214:217], v[114:117]
	v_mfma_f32_16x16x32_bf16 v[102:105], v[172:175], v[222:225], v[102:105]
	v_mfma_f32_16x16x32_bf16 v[98:101], v[206:209], v[222:225], v[98:101]
	v_mfma_f32_16x16x32_bf16 v[86:89], v[172:175], v[230:233], v[86:89]
	v_mfma_f32_16x16x32_bf16 v[82:85], v[206:209], v[230:233], v[82:85]
	v_mfma_f32_16x16x32_bf16 v[70:73], v[172:175], v[238:241], v[70:73]
	v_mfma_f32_16x16x32_bf16 v[66:69], v[206:209], v[238:241], v[66:69]
	s_barrier
	s_add_i32 s10, s23, s79
	s_mov_b32 m0, s10
	ds_read_b128 v[210:213], v201 offset:49152
	ds_read_b128 v[214:217], v201 offset:50176
	ds_read_b128 v[218:221], v201 offset:51200
	ds_read_b128 v[222:225], v201 offset:52224
	ds_read_b128 v[226:229], v201 offset:53248
	ds_read_b128 v[230:233], v201 offset:54272
	ds_read_b128 v[234:237], v201 offset:55296
	ds_read_b128 v[238:241], v201 offset:56320
	global_load_lds_dwordx4 v146, s[98:99]
	s_add_i32 m0, s10, 0x2000
	s_add_i32 s10, s41, s79
	global_load_lds_dwordx4 v150, s[98:99]
	s_add_u32 s98, s98, s76
	s_addc_u32 s99, s99, 0
	s_mov_b32 m0, s10
	s_nop 0
	global_load_lds_dwordx4 v146, s[98:99]
	s_add_i32 m0, s10, 0x2000
	s_nop 0
	global_load_lds_dwordx4 v150, s[98:99]
	s_mov_b32 m0, s26
	s_nop 0
	global_load_lds_dwordx4 v144, s[100:101]
	s_mov_b32 m0, s27
	s_nop 0
	global_load_lds_dwordx4 v148, s[100:101]
	s_waitcnt vmcnt(8)
	s_waitcnt lgkmcnt(0)
	s_barrier
	s_waitcnt lgkmcnt(0)
	v_mfma_f32_16x16x32_bf16 v[62:65], v[130:133], v[210:213], v[62:65]
	v_mfma_f32_16x16x32_bf16 v[58:61], v[160:163], v[210:213], v[58:61]
	v_mfma_f32_16x16x32_bf16 v[46:49], v[130:133], v[218:221], v[46:49]
	v_mfma_f32_16x16x32_bf16 v[42:45], v[160:163], v[218:221], v[42:45]
	v_mfma_f32_16x16x32_bf16 v[30:33], v[130:133], v[226:229], v[30:33]
	v_mfma_f32_16x16x32_bf16 v[26:29], v[160:163], v[226:229], v[26:29]
	v_mfma_f32_16x16x32_bf16 v[14:17], v[130:133], v[234:237], v[14:17]
	v_mfma_f32_16x16x32_bf16 v[10:13], v[160:163], v[234:237], v[10:13]
	v_mfma_f32_16x16x32_bf16 v[62:65], v[134:137], v[214:217], v[62:65]
	v_mfma_f32_16x16x32_bf16 v[58:61], v[164:167], v[214:217], v[58:61]
	v_mfma_f32_16x16x32_bf16 v[46:49], v[134:137], v[222:225], v[46:49]
	v_mfma_f32_16x16x32_bf16 v[42:45], v[164:167], v[222:225], v[42:45]
	v_mfma_f32_16x16x32_bf16 v[30:33], v[134:137], v[230:233], v[30:33]
	v_mfma_f32_16x16x32_bf16 v[26:29], v[164:167], v[230:233], v[26:29]
	v_mfma_f32_16x16x32_bf16 v[14:17], v[134:137], v[238:241], v[14:17]
	v_mfma_f32_16x16x32_bf16 v[10:13], v[164:167], v[238:241], v[10:13]
	v_mfma_f32_16x16x32_bf16 v[54:57], v[168:171], v[210:213], v[54:57]
	v_mfma_f32_16x16x32_bf16 v[50:53], v[202:205], v[210:213], v[50:53]
	v_mfma_f32_16x16x32_bf16 v[38:41], v[168:171], v[218:221], v[38:41]
	v_mfma_f32_16x16x32_bf16 v[34:37], v[202:205], v[218:221], v[34:37]
	v_mfma_f32_16x16x32_bf16 v[22:25], v[168:171], v[226:229], v[22:25]
	v_mfma_f32_16x16x32_bf16 v[18:21], v[202:205], v[226:229], v[18:21]
	v_mfma_f32_16x16x32_bf16 v[6:9], v[168:171], v[234:237], v[6:9]
	v_mfma_f32_16x16x32_bf16 v[2:5], v[202:205], v[234:237], v[2:5]
	v_mfma_f32_16x16x32_bf16 v[54:57], v[172:175], v[214:217], v[54:57]
	v_mfma_f32_16x16x32_bf16 v[50:53], v[206:209], v[214:217], v[50:53]
	v_mfma_f32_16x16x32_bf16 v[38:41], v[172:175], v[222:225], v[38:41]
	v_mfma_f32_16x16x32_bf16 v[34:37], v[206:209], v[222:225], v[34:37]
	v_mfma_f32_16x16x32_bf16 v[22:25], v[172:175], v[230:233], v[22:25]
	v_mfma_f32_16x16x32_bf16 v[18:21], v[206:209], v[230:233], v[18:21]
	v_mfma_f32_16x16x32_bf16 v[6:9], v[172:175], v[238:241], v[6:9]
	v_mfma_f32_16x16x32_bf16 v[2:5], v[206:209], v[238:241], v[2:5]
	s_barrier
	s_add_u32 s2, s2, 0x100
	s_addc_u32 s3, s3, 0
	s_add_u32 s20, s20, 0x100
	s_addc_u32 s21, s21, 0
	s_cmp_ge_u32 s22, s63
	s_mov_b32 s10, s22
	s_cbranch_scc0 .LBB0_294
	v_readlane_b32 s2, v255, 24
	v_readlane_b32 s3, v255, 25
	s_and_b64 vcc, exec, s[2:3]
	s_cbranch_vccz .LBB0_297
	s_barrier

.LBB0_709:
	s_waitcnt vmcnt(0)
	v_readlane_b32 s74, v254, 59
	v_readlane_b32 s44, v255, 38
	v_readlane_b32 s75, v254, 60
	v_readlane_b32 s46, v255, 45
	v_readlane_b32 s45, v255, 39
	v_readlane_b32 s47, v255, 42
	s_setprio 0
	s_barrier
